# adds: attention step loop runs waves 4-7 at priority 1 (static), reset at loop exit
# baseline (speedup 1.0000x reference)
; __device__ __forceinline__ u32x2 ldtr(LAS unsigned char* p) { const v4i16_t v = __builtin_amdgcn_ds_read_tr16_b64_v4i16((LAS v4i16_t*)p); return __builtin_bit_cast(u32x2, v); }
; __device__ __forceinline__ void attn_tile(LAS unsigned char* lds, int bo, const bf16x8 (&qr)[4], f32x16& o0, f32x16& o1, float& mrun, float& lrun, int t, int qlo, int r32, int hi) {
;     ...
;     const int trq = (r32 & 15) >> 2, trp = r32 & 3, blk = r32 >> 4;
;     u32x2 va[4][2][2];
; #pragma unroll
;     for (int st = 0; st < 4; ++st) { const int kvb = 16 * st + 4 * hi;
; #pragma unroll
;         for (int d0 = 0; d0 < 2; ++d0) { va[st][d0][0] = ldtr(lds + bo + 9216 + (kvb + trq) * 144 + (32 * d0 + 16 * blk + 4 * trp) * 2); va[st][d0][1] = ldtr(lds + bo + 9216 + (kvb + 8 + trq) * 144 + (32 * d0 + 16 * blk + 4 * trp) * 2); } }
; __device__ __forceinline__ void attn_unit(LAS unsigned char* lds, const bf16_t* Qp, const bf16_t* Kp, const bf16_t* VTp, int vpitch, const float* CLp, const float* BTp, const float* CMp, const float* KNp, ...
;     ...
;     float mrun = -INFINITY, lrun = 0.f, LB = 0.f;
;     f32x16 o0, o1;
; #pragma unroll
;     for (int r = 0; r < 16; ++r) { o0[r] = 0.f; o1[r] = 0.f; }
;     const int qlo = qpos0 + 32 * wave;
;     int t = NT - 1, bo = 0;
.LBB0_616:
	s_or_b64 exec, exec, s[46:47]
	v_readlane_b32 s8, v243, 1
	v_mov_b32_e32 v5, v1
	v_lshl_add_u64 v[134:135], s[70:71], 0, v[4:5]
	v_mov_b32_e32 v0, s8
	v_add_u32_e32 v0, s5, v0
	s_movk_i32 s5, 0x90
	v_readfirstlane_b32 s35, v0
	v_lshl_add_u64 v[136:137], s[76:77], 0, v[4:5]
	v_add_u32_e32 v4, 31, v0
	v_mad_u32_u24 v153, v3, s5, 0
	v_add_u32_e32 v154, v3, v0
	v_bfe_u32 v0, v2, 2, 2
	v_and_b32_e32 v2, 16, v2
	v_lshlrev_b32_e32 v3, 2, v3
	v_and_or_b32 v2, v3, 12, v2
	v_lshlrev_b32_e32 v155, 1, v2
	v_or_b32_e32 v2, v130, v0
	v_or_b32_e32 v3, 8, v0
	v_mul_lo_u32 v2, v2, s5
	v_add_u32_e32 v156, 0, v2
	v_add_u32_e32 v2, v3, v130
	v_add_u32_e32 v5, 16, v130
	v_mul_lo_u32 v2, v2, s5
	v_add_u32_e32 v157, 0, v2
	v_or_b32_e32 v2, v5, v0
	v_mul_lo_u32 v2, v2, s5
	v_add_u32_e32 v158, 0, v2
	v_add_u32_e32 v2, v5, v3
	v_readfirstlane_b32 s54, v4
	v_add_u32_e32 v4, 32, v130
	v_add_u32_e32 v6, 48, v130
	v_mul_lo_u32 v2, v2, s5
	v_add_u32_e32 v159, 0, v2
	v_or_b32_e32 v2, v4, v0
	v_or_b32_e32 v0, v6, v0
	v_mul_lo_u32 v2, v2, s5
	v_mul_lo_u32 v0, v0, s5
	v_add_u32_e32 v160, 0, v2
	v_add_u32_e32 v2, v4, v3
	v_add_u32_e32 v162, 0, v0
	v_add_u32_e32 v0, v6, v3
	v_mul_lo_u32 v2, v2, s5
	v_mul_lo_u32 v0, v0, s5
	s_lshl_b32 s5, s6, 2
	v_mov_b32_e32 v14, v1
	v_mov_b32_e32 v15, v1
	v_lshlrev_b32_e32 v132, 3, v9
	v_lshlrev_b32_e32 v149, 4, v8
	v_lshlrev_b32_e32 v150, 2, v4
	v_lshlrev_b32_e32 v151, 2, v5
	v_lshlrev_b32_e32 v152, 2, v6
	v_add_u32_e32 v161, 0, v2
	v_add_u32_e32 v163, 0, v0
	s_add_i32 s5, s5, 0
	v_mov_b32_e32 v0, v1
	v_mov_b32_e32 v2, v1
	v_mov_b32_e32 v3, v1
	v_mov_b32_e32 v4, v1
	v_mov_b32_e32 v5, v1
	v_mov_b32_e32 v6, v1
	v_mov_b32_e32 v7, v1
	v_mov_b32_e32 v8, v1
	v_mov_b32_e32 v9, v1
	v_mov_b32_e32 v10, v1
	v_mov_b32_e32 v11, v1
	v_mov_b32_e32 v12, v1
	v_mov_b32_e32 v13, v1
	v_mov_b64_e32 v[30:31], v[14:15]
	v_mov_b64_e32 v[46:47], v[14:15]
	s_add_i32 s55, s5, 0x91f4
	s_add_i32 s56, s12, 0xffffff80
	s_add_i32 s57, s6, -4
	v_mov_b32_e32 v164, 0
	v_mov_b32_e32 v165, 0xff800000
	v_mov_b64_e32 v[28:29], v[12:13]
	v_mov_b64_e32 v[26:27], v[10:11]
	v_mov_b64_e32 v[24:25], v[8:9]
	v_mov_b64_e32 v[22:23], v[6:7]
	v_mov_b64_e32 v[20:21], v[4:5]
	v_mov_b64_e32 v[18:19], v[2:3]
	v_mov_b64_e32 v[16:17], v[0:1]
	v_mov_b64_e32 v[44:45], v[12:13]
	v_mov_b64_e32 v[42:43], v[10:11]
	v_mov_b64_e32 v[40:41], v[8:9]
	v_mov_b64_e32 v[38:39], v[6:7]
	v_mov_b64_e32 v[36:37], v[4:5]
	v_mov_b64_e32 v[34:35], v[2:3]
	v_mov_b64_e32 v[32:33], v[0:1]
	v_mov_b32_e32 v12, 0
	s_waitcnt lgkmcnt(0)
	s_barrier
	v_readfirstlane_b32 s98, v171
	s_cmpk_lt_u32 s98, 0x100
	s_cbranch_scc1 .Lat_noprio
	s_setprio 1
.Lat_noprio:
	s_branch .LBB0_618

; __device__ __forceinline__ float bflo(unsigned w) { return __uint_as_float(w << 16); }
; __device__ __forceinline__ float bfhi(unsigned w) { return __uint_as_float(w & 0xffff0000u); }
; __device__ __forceinline__ void attn_unit(LAS unsigned char* lds, const bf16_t* Qp, const bf16_t* Kp, const bf16_t* VTp, int vpitch, const float* CLp, const float* BTp, const float* CMp, const float* KNp, ...
;     ...
;     if (active) {
;         const float lt = lrun + __shfl_xor(lrun, 32);
;         const float inv = 1.0f / lt;
;         bf16_t* yrow = Yp + (size_t)(32 * wave + r32) * 1024;
; #pragma unroll
;         for (int g = 0; g < 4; ++g) {
;             { bf16_t* p = yrow + 8 * g + 4 * hi; const u32x2 gt = gte[g][0]; u32x2 w;
;               w.x = pk2(o0[4 * g] * inv * bflo(gt.x), o0[4 * g + 1] * inv * bfhi(gt.x)); w.y = pk2(o0[4 * g + 2] * inv * bflo(gt.y), o0[4 * g + 3] * inv * bfhi(gt.y)); *(u32x2*)p = w; }
;             { bf16_t* p = yrow + 32 + 8 * g + 4 * hi; const u32x2 gt = gte[g][1]; u32x2 w;
;               w.x = pk2(o1[4 * g] * inv * bflo(gt.x), o1[4 * g + 1] * inv * bfhi(gt.x)); w.y = pk2(o1[4 * g + 2] * inv * bflo(gt.y), o1[4 * g + 3] * inv * bfhi(gt.y)); *(u32x2*)p = w; }
;         }
;     }
.LBB0_679:
	s_setprio 0
	s_waitcnt vmcnt(0)
	s_andn2_b64 vcc, exec, s[40:41]
	s_cbranch_vccnz .LBB0_681
	ds_bpermute_b32 v0, v140, v164
	v_mov_b32_e32 v113, v1
	s_waitcnt vmcnt(7)
	v_and_b32_e32 v7, 0xffff0000, v128
	v_lshlrev_b32_e32 v8, 16, v129
	v_and_b32_e32 v9, 0xffff0000, v129
	s_waitcnt lgkmcnt(0)
	v_add_f32_e32 v0, v164, v0
	v_div_scale_f32 v2, s[12:13], v0, v0, 1.0
	v_rcp_f32_e32 v3, v2
	s_nop 0
	v_fma_f32 v4, -v2, v3, 1.0
	v_fmac_f32_e32 v3, v4, v3
	v_div_scale_f32 v4, vcc, 1.0, v0, 1.0
	v_mul_f32_e32 v5, v4, v3
	v_fma_f32 v6, -v2, v5, v4
	v_fmac_f32_e32 v5, v6, v3
	v_fma_f32 v2, -v2, v5, v4
	v_div_fmas_f32 v2, v2, v3, v5
	v_div_fixup_f32 v0, v2, v0, 1.0
	v_pk_mul_f32 v[4:5], v[32:33], v[0:1] op_sel_hi:[1,0]
	v_lshlrev_b32_e32 v6, 16, v128
	v_lshlrev_b64 v[2:3], 11, v[112:113]
	v_pk_mul_f32 v[4:5], v[4:5], v[6:7]
	v_pk_mul_f32 v[6:7], v[34:35], v[0:1] op_sel_hi:[1,0]
	v_lshl_add_u64 v[2:3], s[66:67], 0, v[2:3]
	v_pk_mul_f32 v[6:7], v[6:7], v[8:9]
	v_lshl_add_u64 v[2:3], v[130:131], 1, v[2:3]
	v_cvt_pk_bf16_f32 v4, v4, v5
	v_cvt_pk_bf16_f32 v5, v6, v7
	global_store_dwordx2 v[2:3], v[4:5], off
	v_pk_mul_f32 v[4:5], v[16:17], v[0:1] op_sel_hi:[1,0]
	s_waitcnt vmcnt(4)
	v_lshlrev_b32_e32 v6, 16, v126
	v_and_b32_e32 v7, 0xffff0000, v126
	v_pk_mul_f32 v[4:5], v[4:5], v[6:7]
	v_pk_mul_f32 v[6:7], v[18:19], v[0:1] op_sel_hi:[1,0]
	v_lshlrev_b32_e32 v8, 16, v127
	v_and_b32_e32 v9, 0xffff0000, v127
	v_pk_mul_f32 v[6:7], v[6:7], v[8:9]
	v_cvt_pk_bf16_f32 v4, v4, v5
	v_cvt_pk_bf16_f32 v5, v6, v7
	global_store_dwordx2 v[2:3], v[4:5], off offset:64
	v_pk_mul_f32 v[4:5], v[36:37], v[0:1] op_sel_hi:[1,0]
	v_lshlrev_b32_e32 v6, 16, v124
	v_and_b32_e32 v7, 0xffff0000, v124
	v_pk_mul_f32 v[4:5], v[4:5], v[6:7]
	v_pk_mul_f32 v[6:7], v[38:39], v[0:1] op_sel_hi:[1,0]
	v_lshlrev_b32_e32 v8, 16, v125
	v_and_b32_e32 v9, 0xffff0000, v125
	v_pk_mul_f32 v[6:7], v[6:7], v[8:9]
	v_cvt_pk_bf16_f32 v4, v4, v5
	v_cvt_pk_bf16_f32 v5, v6, v7
	global_store_dwordx2 v[2:3], v[4:5], off offset:16
	v_pk_mul_f32 v[4:5], v[20:21], v[0:1] op_sel_hi:[1,0]
	s_waitcnt vmcnt(5)
	v_lshlrev_b32_e32 v6, 16, v122
	v_and_b32_e32 v7, 0xffff0000, v122
	v_pk_mul_f32 v[4:5], v[4:5], v[6:7]
	v_pk_mul_f32 v[6:7], v[22:23], v[0:1] op_sel_hi:[1,0]
	v_lshlrev_b32_e32 v8, 16, v123
	v_and_b32_e32 v9, 0xffff0000, v123
	v_pk_mul_f32 v[6:7], v[6:7], v[8:9]
	v_cvt_pk_bf16_f32 v4, v4, v5
	v_cvt_pk_bf16_f32 v5, v6, v7
	global_store_dwordx2 v[2:3], v[4:5], off offset:80
	v_pk_mul_f32 v[4:5], v[40:41], v[0:1] op_sel_hi:[1,0]
	v_lshlrev_b32_e32 v6, 16, v120
	v_and_b32_e32 v7, 0xffff0000, v120
	v_pk_mul_f32 v[4:5], v[4:5], v[6:7]
	v_pk_mul_f32 v[6:7], v[42:43], v[0:1] op_sel_hi:[1,0]
	v_lshlrev_b32_e32 v8, 16, v121
	v_and_b32_e32 v9, 0xffff0000, v121
	v_pk_mul_f32 v[6:7], v[6:7], v[8:9]
	v_cvt_pk_bf16_f32 v4, v4, v5
	v_cvt_pk_bf16_f32 v5, v6, v7
	global_store_dwordx2 v[2:3], v[4:5], off offset:32
	v_pk_mul_f32 v[4:5], v[24:25], v[0:1] op_sel_hi:[1,0]
	s_waitcnt vmcnt(6)
	v_lshlrev_b32_e32 v6, 16, v118
	v_and_b32_e32 v7, 0xffff0000, v118
	v_pk_mul_f32 v[4:5], v[4:5], v[6:7]
	v_pk_mul_f32 v[6:7], v[26:27], v[0:1] op_sel_hi:[1,0]
	v_lshlrev_b32_e32 v8, 16, v119
	v_and_b32_e32 v9, 0xffff0000, v119
	v_pk_mul_f32 v[6:7], v[6:7], v[8:9]
	v_cvt_pk_bf16_f32 v4, v4, v5
	v_cvt_pk_bf16_f32 v5, v6, v7
	global_store_dwordx2 v[2:3], v[4:5], off offset:96
	v_pk_mul_f32 v[4:5], v[44:45], v[0:1] op_sel_hi:[1,0]
	v_lshlrev_b32_e32 v6, 16, v116
	v_and_b32_e32 v7, 0xffff0000, v116
	v_pk_mul_f32 v[4:5], v[4:5], v[6:7]
	v_pk_mul_f32 v[6:7], v[46:47], v[0:1] op_sel_hi:[1,0]
	v_lshlrev_b32_e32 v8, 16, v117
	v_and_b32_e32 v9, 0xffff0000, v117
	v_pk_mul_f32 v[6:7], v[6:7], v[8:9]
	v_cvt_pk_bf16_f32 v4, v4, v5
	v_cvt_pk_bf16_f32 v5, v6, v7
	global_store_dwordx2 v[2:3], v[4:5], off offset:48
	v_pk_mul_f32 v[4:5], v[28:29], v[0:1] op_sel_hi:[1,0]
	s_waitcnt vmcnt(7)
	v_lshlrev_b32_e32 v6, 16, v114
	v_and_b32_e32 v7, 0xffff0000, v114
	v_pk_mul_f32 v[4:5], v[4:5], v[6:7]
	v_pk_mul_f32 v[6:7], v[30:31], v[0:1] op_sel_hi:[1,0]
	v_lshlrev_b32_e32 v8, 16, v115
	v_and_b32_e32 v9, 0xffff0000, v115
	v_pk_mul_f32 v[6:7], v[6:7], v[8:9]
	v_cvt_pk_bf16_f32 v4, v4, v5
	v_cvt_pk_bf16_f32 v5, v6, v7
	global_store_dwordx2 v[2:3], v[4:5], off offset:112
